# dense attention item loop shifted +16 bytes (loop-head offset 12 mod 64), complementary pad after the phase
# speedup vs baseline: 1.0107x; 1.0042x over previous
; DI int fresh_lane() { int l; asm volatile("v_mbcnt_lo_u32_b32 %0, -1, 0\n\tv_mbcnt_hi_u32_b32 %0, -1, %0" : "=v"(l)); return l; }
; #define FRESH_IDS() int tid_ = wave_s * 64 + fresh_lane(); asm volatile("" : "+v"(tid_)); const int tid = tid_, lane = tid & 63, wave = wave_s; (void)tid; (void)lane; (void)wave
; __global__ void __launch_bounds__(512, 2) fwd_kernel(Params p) {
;     ...
;     for (int rep_ = 0; rep_ < REP_ATTNC; ++rep_) { FRESH_IDS();
;         const int G_ = (int)gridDim.x, vcu = (G_ % 8 == 0) ? ((int)blockIdx.x & 7) * (G_ >> 3) + ((int)blockIdx.x >> 3) : (int)blockIdx.x;
;         for (int item = vcu; item < 1024; item += G_) {
;             const int qb = item & 15, head = (item >> 4) & 7, b = item >> 7, kvh = head >> 2;
;             int tl = wave * 64 + fresh_lane(); asm volatile("" : "+v"(tl));
;             const size_t qrow = (size_t)NCTX + (size_t)b * SEQ + qb * 256;
;             __syncthreads();
.LBB0_1525:
	s_or_b64 exec, exec, s[0:1]
	s_and_b32 s1, s75, 7
	s_ashr_i32 s2, s30, 3
	s_mul_i32 s1, s2, s1
	s_ashr_i32 s2, s75, 3
	s_and_b32 s0, s30, 7
	s_add_i32 s1, s1, s2
	s_cmp_eq_u32 s0, 0
	s_waitcnt lgkmcnt(0)
	s_barrier
	v_mbcnt_lo_u32_b32 v0, -1, 0
	v_mbcnt_hi_u32_b32 v0, -1, v0
	s_cselect_b32 s2, s1, s75
	s_mov_b32 s56, 0
	v_add_u32_e32 v0, s74, v0
	s_cmpk_gt_i32 s2, 0x3ff
	s_cbranch_scc1 .LBB0_1547
	s_add_u32 s3, s28, 0x1e500000
	s_addc_u32 s11, s29, 0
	s_add_u32 s0, s28, 0x1e512000
	s_addc_u32 s1, s29, 0
	v_mov_b32_e32 v177, 0
	s_mov_b32 s14, 0x42b504f3
	s_mov_b32 s10, 0x3e0293ee
	v_mov_b32_e32 v180, 0xf149f2ca
	s_mov_b64 s[12:13], 0x8000
	v_mov_b32_e32 v181, 0x110000
	s_nop 0
	s_nop 0
	s_nop 0
	s_nop 0
	s_branch .LBB0_1528

; DI void xcd_barrier(const XcdBarrier& b, int tid) {
;     asm volatile("s_waitcnt vmcnt(0)" ::: "memory");
;     __syncthreads();
;     if (tid == 0) {
;         unsigned* bar = b.bar;
;         __builtin_amdgcn_s_waitcnt(0);
;         unsigned nloc = b.st[0], nx = b.st[1];
;         if (nloc == 0u) { xcd_barrier_complete(bar, b.x, nloc, nx); b.st[0] = nloc; b.st[1] = nx; }
.LBB0_1547:
	s_nop 0
	s_nop 0
	s_nop 0
	s_nop 0
	s_nop 0
	s_nop 0
	s_nop 0
	s_nop 0
	s_nop 0
	s_nop 0
	s_nop 0
	s_nop 0
	v_mbcnt_lo_u32_b32 v0, -1, 0
	v_mbcnt_hi_u32_b32 v0, -1, v0
	s_nop 0
	v_add_u32_e32 v0, s74, v0
	s_waitcnt vmcnt(0)
	s_waitcnt vmcnt(63) expcnt(7) lgkmcnt(15)
	v_cmp_eq_u32_e32 vcc, 0, v0
	s_barrier
	s_and_saveexec_b64 s[0:1], vcc
	v_readlane_b32 s59, v254, 12
	s_cbranch_execz .LBB0_1599
	s_add_i32 s2, 0, 0x23ff0
	v_mov_b32_e32 v0, s2
	s_waitcnt vmcnt(0) expcnt(0) lgkmcnt(0)
	ds_read_b32 v2, v0
	s_add_i32 s2, 0, 0x23ff4
	v_mov_b32_e32 v0, s2
	ds_read_b32 v0, v0
	s_waitcnt lgkmcnt(1)
	v_cmp_ne_u32_e32 vcc, 0, v2
	s_cbranch_vccnz .LBB0_1563
	s_mov_b32 s2, 1
	v_mov_b32_e32 v16, 0
	s_branch .LBB0_1551
